# attention QK: interleave the two accumulation chains
# baseline (speedup 1.0000x reference)
; DI void attn_item(const u16* __restrict__ qbuf, const u16* __restrict__ knope, const u16* __restrict__ krope, ...
;     ...
;   for (int kt = 0; kt < ntiles; ++kt) {
;     asm volatile("s_waitcnt vmcnt(0)" ::: "memory");
;     __syncthreads();
;     if (kt + 1 < ntiles) ATT_DMA((unsigned)((kt + 1) & 1) * 40960u)
;     if (active && kt < my_tiles) {
;       const char* cur = smem + (kt & 1) * 40960;
;       f32x16 st[2];
; #pragma unroll
;       for (int mt = 0; mt < 2; ++mt) {
; #pragma unroll
;         for (int j = 0; j < 16; ++j) st[mt][j] = 0.f;
; #pragma unroll
;         for (int ks = 0; ks < 12; ++ks) {
;           const bf16x8 kf = *(const bf16x8*)(cur + koff[ks & 3] + (ks >> 2) * 8192 + mt * 4096);
;           st[mt] = __builtin_amdgcn_mfma_f32_32x32x16_bf16(kf, qf[ks], st[mt], 0, 0, 0);
;         }
;       }
;       if (kt * 64 + 64 > nkeys) {
; #pragma unroll
;         for (int mt = 0; mt < 2; ++mt)
; #pragma unroll
;           for (int j = 0; j < 16; ++j) {
;             const int key = kt * 64 + mt * 32 + (j & 3) + 8 * (j >> 2) + 4 * h2;
;             if (key >= nkeys) st[mt][j] = -INFINITY;
;           }
;       }
;       float mx = fmaxf(st[0][0], st[1][0]);
; #pragma unroll
;       for (int j = 1; j < 16; ++j) mx = fmaxf(mx, fmaxf(st[0][j], st[1][j]));
;       mx = fmaxf(mx, __shfl_xor(mx, 32, 64));
;       const float m_new = fmaxf(m_run, mx);
;       const float alpha = __builtin_amdgcn_exp2f(m_run - m_new);
;       m_run = m_new;
.LBB0_46:
	s_add_i32 s10, s11, 1
	s_bitcmp1_b32 s10, 0
	v_add_u32_e32 v66, v152, v154
	s_cselect_b32 s12, 0xa000, 0
	v_add_u32_e32 v182, 0x1010000, v66
	v_add_u32_e32 v67, v153, v154
	s_waitcnt vmcnt(0)
	s_barrier
	s_add_i32 s13, s12, s7
	v_lshl_add_u64 v[64:65], v[182:183], 1, s[92:93]
	s_mov_b32 m0, s13
	s_nop 0
	global_load_lds_dwordx4 v[64:65], off
	v_add_u32_e32 v182, 0x1012000, v67
	v_lshl_add_u64 v[64:65], v[182:183], 1, s[92:93]
	s_add_i32 s14, s13, 0x400
	s_mov_b32 m0, s14
	s_nop 0
	global_load_lds_dwordx4 v[64:65], off
	v_add_u32_e32 v182, 0x1014000, v66
	v_lshl_add_u64 v[64:65], v[182:183], 1, s[92:93]
	s_add_i32 s14, s13, 0x800
	s_mov_b32 m0, s14
	s_nop 0
	global_load_lds_dwordx4 v[64:65], off
	v_add_u32_e32 v182, 0x1016000, v67
	s_mov_b32 s2, 0x101000
	v_lshl_add_u64 v[64:65], v[182:183], 1, s[92:93]
	s_addk_i32 s13, 0xc00
	s_mov_b32 m0, s13
	s_nop 0
	global_load_lds_dwordx4 v[64:65], off
	v_add3_u32 v182, v152, v155, s2
	s_mov_b32 s2, 0x101200
	s_add_i32 s13, s12, s8
	v_lshl_add_u64 v[64:65], v[182:183], 1, s[30:31]
	s_mov_b32 m0, s13
	s_nop 0
	global_load_lds_dwordx4 v[64:65], off
	v_add3_u32 v182, v153, v155, s2
	v_add_u32_e32 v66, v152, v156
	v_lshl_add_u64 v[64:65], v[182:183], 1, s[30:31]
	s_addk_i32 s13, 0x400
	s_mov_b32 m0, s13
	s_nop 0
	global_load_lds_dwordx4 v[64:65], off
	v_add_u32_e32 v182, 64, v66
	v_add_u32_e32 v67, v153, v156
	s_add_i32 s12, s12, s9
	v_lshl_add_u64 v[64:65], v[182:183], 1, s[40:41]
	s_mov_b32 m0, s12
	s_nop 0
	global_load_lds_dwordx4 v[64:65], off
	v_add_u32_e32 v182, 0x2440, v67
	v_lshl_add_u64 v[64:65], v[182:183], 1, s[40:41]
	s_add_i32 s13, s12, 0x400
	s_mov_b32 m0, s13
	s_nop 0
	global_load_lds_dwordx4 v[64:65], off
	v_add_u32_e32 v182, 0x4840, v66
	v_lshl_add_u64 v[64:65], v[182:183], 1, s[40:41]
	s_add_i32 s13, s12, 0x800
	s_mov_b32 m0, s13
	s_nop 0
	global_load_lds_dwordx4 v[64:65], off
	v_add_u32_e32 v182, 0x6c40, v67
	v_lshl_add_u64 v[64:65], v[182:183], 1, s[40:41]
	s_addk_i32 s12, 0xc00
	s_mov_b32 m0, s12
	s_nop 0
	global_load_lds_dwordx4 v[64:65], off
	s_and_saveexec_b64 s[42:43], s[38:39]
	s_cbranch_execz .LBB0_50
	s_bitcmp1_b32 s11, 0
	s_cselect_b32 s11, 0xa000, 0
	v_or_b32_e32 v157, s11, v150
	v_or_b32_e32 v162, s11, v149
	v_or_b32_e32 v163, s11, v148
	v_or_b32_e32 v164, s11, v145
	ds_read_b128 v[224:227], v157
	ds_read_b128 v[228:231], v157 offset:4096
	ds_read_b128 v[232:235], v162
	ds_read_b128 v[236:239], v162 offset:4096
	ds_read_b128 v[240:243], v163
	ds_read_b128 v[244:247], v163 offset:4096
	ds_read_b128 v[248:251], v164
	ds_read_b128 v[186:189], v164 offset:4096
	s_waitcnt lgkmcnt(7)
	v_mfma_f32_32x32x16_bf16 v[64:79], v[224:227], v[140:143], 0
	ds_read_b128 v[224:227], v157 offset:8192
	s_waitcnt lgkmcnt(7)
	v_mfma_f32_32x32x16_bf16 v[80:95], v[228:231], v[140:143], 0
	ds_read_b128 v[228:231], v157 offset:12288
	s_waitcnt lgkmcnt(7)
	v_mfma_f32_32x32x16_bf16 v[64:79], v[232:235], v[136:139], v[64:79]
	ds_read_b128 v[232:235], v162 offset:8192
	s_waitcnt lgkmcnt(7)
	v_mfma_f32_32x32x16_bf16 v[80:95], v[236:239], v[136:139], v[80:95]
	ds_read_b128 v[236:239], v162 offset:12288
	s_waitcnt lgkmcnt(7)
	v_mfma_f32_32x32x16_bf16 v[64:79], v[240:243], v[132:135], v[64:79]
	ds_read_b128 v[240:243], v163 offset:8192
	s_waitcnt lgkmcnt(7)
	v_mfma_f32_32x32x16_bf16 v[80:95], v[244:247], v[132:135], v[80:95]
	ds_read_b128 v[244:247], v163 offset:12288
	s_waitcnt lgkmcnt(7)
	v_mfma_f32_32x32x16_bf16 v[64:79], v[248:251], v[128:131], v[64:79]
	ds_read_b128 v[248:251], v164 offset:8192
	s_waitcnt lgkmcnt(7)
	v_mfma_f32_32x32x16_bf16 v[80:95], v[186:189], v[128:131], v[80:95]
	ds_read_b128 v[186:189], v164 offset:12288
	s_waitcnt lgkmcnt(7)
	v_mfma_f32_32x32x16_bf16 v[64:79], v[224:227], v[124:127], v[64:79]
	ds_read_b128 v[224:227], v157 offset:16384
	s_waitcnt lgkmcnt(7)
	v_mfma_f32_32x32x16_bf16 v[80:95], v[228:231], v[124:127], v[80:95]
	ds_read_b128 v[228:231], v157 offset:20480
	s_waitcnt lgkmcnt(7)
	v_mfma_f32_32x32x16_bf16 v[64:79], v[232:235], v[120:123], v[64:79]
	ds_read_b128 v[232:235], v162 offset:16384
	s_waitcnt lgkmcnt(7)
	v_mfma_f32_32x32x16_bf16 v[80:95], v[236:239], v[120:123], v[80:95]
	ds_read_b128 v[236:239], v162 offset:20480
	s_waitcnt lgkmcnt(7)
	v_mfma_f32_32x32x16_bf16 v[64:79], v[240:243], v[116:119], v[64:79]
	ds_read_b128 v[240:243], v163 offset:16384
	s_waitcnt lgkmcnt(7)
	v_mfma_f32_32x32x16_bf16 v[80:95], v[244:247], v[116:119], v[80:95]
	ds_read_b128 v[244:247], v163 offset:20480
	s_waitcnt lgkmcnt(7)
	v_mfma_f32_32x32x16_bf16 v[64:79], v[248:251], v[112:115], v[64:79]
	ds_read_b128 v[248:251], v164 offset:16384
	s_waitcnt lgkmcnt(7)
	v_mfma_f32_32x32x16_bf16 v[80:95], v[186:189], v[112:115], v[80:95]
	ds_read_b128 v[186:189], v164 offset:20480
	s_waitcnt lgkmcnt(7)
	v_mfma_f32_32x32x16_bf16 v[64:79], v[224:227], v[108:111], v[64:79]
	ds_read_b128 v[224:227], v157 offset:24576
	s_waitcnt lgkmcnt(7)
	v_mfma_f32_32x32x16_bf16 v[80:95], v[228:231], v[108:111], v[80:95]
	ds_read_b128 v[228:231], v157 offset:28672
	s_waitcnt lgkmcnt(7)
	v_mfma_f32_32x32x16_bf16 v[64:79], v[232:235], v[104:107], v[64:79]
	ds_read_b128 v[232:235], v157 offset:32768
	s_waitcnt lgkmcnt(7)
	v_mfma_f32_32x32x16_bf16 v[80:95], v[236:239], v[104:107], v[80:95]
	ds_read_b128 v[236:239], v157 offset:36864
	s_waitcnt lgkmcnt(7)
	v_mfma_f32_32x32x16_bf16 v[64:79], v[240:243], v[100:103], v[64:79]
	ds_read_b128 v[240:243], v162 offset:24576
	s_waitcnt lgkmcnt(7)
	v_mfma_f32_32x32x16_bf16 v[80:95], v[244:247], v[100:103], v[80:95]
	ds_read_b128 v[244:247], v162 offset:28672
	s_waitcnt lgkmcnt(7)
	v_mfma_f32_32x32x16_bf16 v[64:79], v[248:251], v[96:99], v[64:79]
	ds_read_b128 v[248:251], v162 offset:32768
	s_waitcnt lgkmcnt(7)
	v_mfma_f32_32x32x16_bf16 v[80:95], v[186:189], v[96:99], v[80:95]
	ds_read_b128 v[186:189], v162 offset:36864
	s_nop 1
	s_nop 9
	v_max3_f32 v158, v64, v65, v66
	v_max3_f32 v159, v67, v68, v69
	v_max3_f32 v158, v158, v70, v71
	v_max3_f32 v159, v159, v72, v73
	v_max3_f32 v158, v158, v74, v75
	v_max3_f32 v159, v159, v76, v77
	v_max3_f32 v158, v158, v78, v79
	v_max_f32_e32 v158, v158, v159
	s_nop 1
	v_max3_f32 v159, v80, v81, v82
	v_max3_f32 v160, v83, v84, v85
	v_max3_f32 v159, v159, v86, v87
	v_max3_f32 v160, v160, v88, v89
	v_max3_f32 v159, v159, v90, v91
	v_max3_f32 v160, v160, v92, v93
	v_max3_f32 v159, v159, v94, v95
	v_max3_f32 v158, v158, v159, v160
	v_mov_b32_e32 v159, v158
	s_nop 1
	v_permlane32_swap_b32_e32 v158, v159
	v_max3_f32 v157, v146, v158, v159
	v_sub_f32_e32 v158, v146, v157
	v_cmp_gt_f32_e32 vcc, 0xc1000000, v158
	s_cbranch_vccnz .Lattn_resc_49
	v_mov_b32_e32 v157, v146
	v_mov_b32_e32 v146, 1.0
	s_branch .LBB0_49

; DI void attn_item(const u16* __restrict__ qbuf, const u16* __restrict__ knope, const u16* __restrict__ krope, ...
;     ...
;     if (active && kt < my_tiles) {
;       const char* cur = smem + (kt & 1) * 40960;
;       f32x16 st[2];
; #pragma unroll
;       for (int mt = 0; mt < 2; ++mt) {
; #pragma unroll
;         for (int j = 0; j < 16; ++j) st[mt][j] = 0.f;
; #pragma unroll
;         for (int ks = 0; ks < 12; ++ks) {
;           const bf16x8 kf = *(const bf16x8*)(cur + koff[ks & 3] + (ks >> 2) * 8192 + mt * 4096);
;           st[mt] = __builtin_amdgcn_mfma_f32_32x32x16_bf16(kf, qf[ks], st[mt], 0, 0, 0);
;         }
;       }
;       if (kt * 64 + 64 > nkeys) {
.LBB0_68:
	s_bitcmp1_b32 s17, 0
	s_cselect_b32 s17, 0xa000, 0
	v_or_b32_e32 v165, s17, v149
	v_or_b32_e32 v170, s17, v150
	v_or_b32_e32 v171, s17, v151
	v_or_b32_e32 v172, s17, v152
	ds_read_b128 v[224:227], v165
	ds_read_b128 v[228:231], v165 offset:4096
	ds_read_b128 v[232:235], v170
	ds_read_b128 v[236:239], v170 offset:4096
	ds_read_b128 v[240:243], v171
	ds_read_b128 v[244:247], v171 offset:4096
	ds_read_b128 v[248:251], v172
	ds_read_b128 v[186:189], v172 offset:4096
	s_waitcnt lgkmcnt(7)
	v_mfma_f32_32x32x16_bf16 v[64:79], v[224:227], v[140:143], 0
	ds_read_b128 v[224:227], v165 offset:8192
	s_waitcnt lgkmcnt(7)
	v_mfma_f32_32x32x16_bf16 v[80:95], v[228:231], v[140:143], 0
	ds_read_b128 v[228:231], v165 offset:12288
	s_waitcnt lgkmcnt(7)
	v_mfma_f32_32x32x16_bf16 v[64:79], v[232:235], v[136:139], v[64:79]
	ds_read_b128 v[232:235], v170 offset:8192
	s_waitcnt lgkmcnt(7)
	v_mfma_f32_32x32x16_bf16 v[80:95], v[236:239], v[136:139], v[80:95]
	ds_read_b128 v[236:239], v170 offset:12288
	s_waitcnt lgkmcnt(7)
	v_mfma_f32_32x32x16_bf16 v[64:79], v[240:243], v[132:135], v[64:79]
	ds_read_b128 v[240:243], v171 offset:8192
	s_waitcnt lgkmcnt(7)
	v_mfma_f32_32x32x16_bf16 v[80:95], v[244:247], v[132:135], v[80:95]
	ds_read_b128 v[244:247], v171 offset:12288
	s_waitcnt lgkmcnt(7)
	v_mfma_f32_32x32x16_bf16 v[64:79], v[248:251], v[128:131], v[64:79]
	ds_read_b128 v[248:251], v172 offset:8192
	s_waitcnt lgkmcnt(7)
	v_mfma_f32_32x32x16_bf16 v[80:95], v[186:189], v[128:131], v[80:95]
	ds_read_b128 v[186:189], v172 offset:12288
	s_waitcnt lgkmcnt(7)
	v_mfma_f32_32x32x16_bf16 v[64:79], v[224:227], v[124:127], v[64:79]
	ds_read_b128 v[224:227], v165 offset:16384
	s_waitcnt lgkmcnt(7)
	v_mfma_f32_32x32x16_bf16 v[80:95], v[228:231], v[124:127], v[80:95]
	ds_read_b128 v[228:231], v165 offset:20480
	s_waitcnt lgkmcnt(7)
	v_mfma_f32_32x32x16_bf16 v[64:79], v[232:235], v[120:123], v[64:79]
	ds_read_b128 v[232:235], v170 offset:16384
	s_waitcnt lgkmcnt(7)
	v_mfma_f32_32x32x16_bf16 v[80:95], v[236:239], v[120:123], v[80:95]
	ds_read_b128 v[236:239], v170 offset:20480
	s_waitcnt lgkmcnt(7)
	v_mfma_f32_32x32x16_bf16 v[64:79], v[240:243], v[116:119], v[64:79]
	ds_read_b128 v[240:243], v171 offset:16384
	s_waitcnt lgkmcnt(7)
	v_mfma_f32_32x32x16_bf16 v[80:95], v[244:247], v[116:119], v[80:95]
	ds_read_b128 v[244:247], v171 offset:20480
	s_waitcnt lgkmcnt(7)
	v_mfma_f32_32x32x16_bf16 v[64:79], v[248:251], v[112:115], v[64:79]
	ds_read_b128 v[248:251], v172 offset:16384
	s_waitcnt lgkmcnt(7)
	v_mfma_f32_32x32x16_bf16 v[80:95], v[186:189], v[112:115], v[80:95]
	ds_read_b128 v[186:189], v172 offset:20480
	s_waitcnt lgkmcnt(7)
	v_mfma_f32_32x32x16_bf16 v[64:79], v[224:227], v[108:111], v[64:79]
	ds_read_b128 v[224:227], v165 offset:24576
	s_waitcnt lgkmcnt(7)
	v_mfma_f32_32x32x16_bf16 v[80:95], v[228:231], v[108:111], v[80:95]
	ds_read_b128 v[228:231], v165 offset:28672
	s_waitcnt lgkmcnt(7)
	v_mfma_f32_32x32x16_bf16 v[64:79], v[232:235], v[104:107], v[64:79]
	ds_read_b128 v[232:235], v165 offset:32768
	s_waitcnt lgkmcnt(7)
	v_mfma_f32_32x32x16_bf16 v[80:95], v[236:239], v[104:107], v[80:95]
	ds_read_b128 v[236:239], v165 offset:36864
	s_waitcnt lgkmcnt(7)
	v_mfma_f32_32x32x16_bf16 v[64:79], v[240:243], v[100:103], v[64:79]
	ds_read_b128 v[240:243], v170 offset:24576
	s_waitcnt lgkmcnt(7)
	v_mfma_f32_32x32x16_bf16 v[80:95], v[244:247], v[100:103], v[80:95]
	ds_read_b128 v[244:247], v170 offset:28672
	s_waitcnt lgkmcnt(7)
	v_mfma_f32_32x32x16_bf16 v[64:79], v[248:251], v[96:99], v[64:79]
	ds_read_b128 v[248:251], v170 offset:32768
	s_waitcnt lgkmcnt(7)
	v_mfma_f32_32x32x16_bf16 v[80:95], v[186:189], v[96:99], v[80:95]
	ds_read_b128 v[186:189], v170 offset:36864
	s_cmp_lt_i32 s15, s14
	s_cbranch_scc1 .LBB0_70
; DI void attn_item(const u16* __restrict__ qbuf, const u16* __restrict__ knope, const u16* __restrict__ krope, ...
;     ...
;       if (kt * 64 + 64 > nkeys) {
; #pragma unroll
;         for (int mt = 0; mt < 2; ++mt)
; #pragma unroll
;           for (int j = 0; j < 16; ++j) {
;             const int key = kt * 64 + mt * 32 + (j & 3) + 8 * (j >> 2) + 4 * h2;
;             if (key >= nkeys) st[mt][j] = -INFINITY;
;           }
;       }
;       float mx = fmaxf(st[0][0], st[1][0]);
; #pragma unroll
;       for (int j = 1; j < 16; ++j) mx = fmaxf(mx, fmaxf(st[0][j], st[1][j]));
;       mx = fmaxf(mx, __shfl_xor(mx, 32, 64));
;       const float m_new = fmaxf(m_run, mx);
;       const float alpha = __builtin_amdgcn_exp2f(m_run - m_new);
;       m_run = m_new;
	v_add_u32_e32 v165, s15, v156
	v_add_u32_e32 v166, 1, v165
	v_cmp_gt_i32_e32 vcc, s14, v165
	v_cmp_gt_i32_e64 s[40:41], s14, v166
	s_or_b64 vcc, s[40:41], vcc
	v_add_u32_e32 v166, 2, v165
	v_cndmask_b32_e32 v64, v212, v64, vcc
	v_cmp_gt_i32_e32 vcc, s14, v166
	v_add_u32_e32 v166, 3, v165
	v_cndmask_b32_e64 v65, v212, v65, s[40:41]
	v_cndmask_b32_e32 v66, v212, v66, vcc
	v_cmp_gt_i32_e32 vcc, s14, v166
	v_add_u32_e32 v166, 8, v165
	s_nop 0
	v_cndmask_b32_e32 v67, v212, v67, vcc
	v_cmp_gt_i32_e32 vcc, s14, v166
	v_add_u32_e32 v166, 9, v165
	s_nop 0
	v_cndmask_b32_e32 v68, v212, v68, vcc
	v_cmp_gt_i32_e32 vcc, s14, v166
	v_add_u32_e32 v166, 10, v165
	s_nop 0
	v_cndmask_b32_e32 v69, v212, v69, vcc
	v_cmp_gt_i32_e32 vcc, s14, v166
	v_add_u32_e32 v166, 11, v165
	s_nop 0
	v_cndmask_b32_e32 v70, v212, v70, vcc
	v_cmp_gt_i32_e32 vcc, s14, v166
	v_add_u32_e32 v166, 16, v165
	s_nop 0
	v_cndmask_b32_e32 v71, v212, v71, vcc
	v_cmp_gt_i32_e32 vcc, s14, v166
	v_add_u32_e32 v166, 17, v165
	s_nop 0
	v_cndmask_b32_e32 v72, v212, v72, vcc
	v_cmp_gt_i32_e32 vcc, s14, v166
	v_add_u32_e32 v166, 18, v165
	s_nop 0
	v_cndmask_b32_e32 v73, v212, v73, vcc
	v_cmp_gt_i32_e32 vcc, s14, v166
	v_add_u32_e32 v166, 19, v165
	s_nop 0
	v_cndmask_b32_e32 v74, v212, v74, vcc
	v_cmp_gt_i32_e32 vcc, s14, v166
	v_add_u32_e32 v166, 24, v165
	s_nop 0
	v_cndmask_b32_e32 v75, v212, v75, vcc
	v_cmp_gt_i32_e32 vcc, s14, v166
	v_add_u32_e32 v166, 25, v165
	s_nop 0
	v_cndmask_b32_e32 v76, v212, v76, vcc
	v_cmp_gt_i32_e32 vcc, s14, v166
	v_add_u32_e32 v166, 26, v165
	s_nop 0
	v_cndmask_b32_e32 v77, v212, v77, vcc
	v_cmp_gt_i32_e32 vcc, s14, v166
	v_add_u32_e32 v166, 27, v165
	s_nop 0
	v_cndmask_b32_e32 v78, v212, v78, vcc
	v_cmp_gt_i32_e32 vcc, s14, v166
	v_add_u32_e32 v166, 32, v165
	v_cmp_gt_i32_e64 s[40:41], s14, v166
	v_add_u32_e32 v166, 33, v165
	v_cmp_gt_i32_e64 s[42:43], s14, v166
	v_add_u32_e32 v166, 34, v165
	v_cmp_gt_i32_e64 s[44:45], s14, v166
	v_add_u32_e32 v166, 35, v165
	v_cmp_gt_i32_e64 s[46:47], s14, v166
	v_add_u32_e32 v166, 40, v165
	v_cmp_gt_i32_e64 s[48:49], s14, v166
	v_add_u32_e32 v166, 41, v165
	v_cmp_gt_i32_e64 s[50:51], s14, v166
	v_add_u32_e32 v166, 42, v165
	v_cmp_gt_i32_e64 s[52:53], s14, v166
	v_add_u32_e32 v166, 43, v165
	v_cmp_gt_i32_e64 s[56:57], s14, v166
	v_add_u32_e32 v166, 48, v165
	v_cmp_gt_i32_e64 s[58:59], s14, v166
	v_add_u32_e32 v166, 49, v165
	v_cmp_gt_i32_e64 s[60:61], s14, v166
	v_add_u32_e32 v166, 50, v165
	v_cmp_gt_i32_e64 s[62:63], s14, v166
	v_add_u32_e32 v166, 51, v165
	v_cmp_gt_i32_e64 s[64:65], s14, v166
	v_add_u32_e32 v166, 56, v165
	v_cmp_gt_i32_e64 s[66:67], s14, v166
	v_add_u32_e32 v166, 57, v165
	v_cmp_gt_i32_e64 s[68:69], s14, v166
	v_add_u32_e32 v166, 58, v165
	v_add_u32_e32 v165, 59, v165
	v_cmp_gt_i32_e64 s[70:71], s14, v166
	v_cmp_gt_i32_e64 s[72:73], s14, v165
	s_or_b64 s[70:71], s[72:73], s[70:71]
	s_or_b64 s[68:69], s[70:71], s[68:69]
	s_or_b64 s[66:67], s[68:69], s[66:67]
	s_or_b64 s[64:65], s[66:67], s[64:65]
	s_or_b64 s[62:63], s[64:65], s[62:63]
	s_or_b64 s[60:61], s[62:63], s[60:61]
	s_or_b64 s[58:59], s[60:61], s[58:59]
	s_or_b64 s[56:57], s[58:59], s[56:57]
	s_or_b64 s[52:53], s[56:57], s[52:53]
	s_or_b64 s[50:51], s[52:53], s[50:51]
	s_or_b64 s[48:49], s[50:51], s[48:49]
	s_or_b64 s[46:47], s[48:49], s[46:47]
	s_or_b64 s[44:45], s[46:47], s[44:45]
	s_or_b64 s[42:43], s[44:45], s[42:43]
	s_or_b64 s[40:41], s[42:43], s[40:41]
	s_or_b64 vcc, s[40:41], vcc
	v_cndmask_b32_e64 v95, v212, v95, s[72:73]
	v_cndmask_b32_e64 v94, v212, v94, s[70:71]
	s_mov_b64 s[70:71], s[26:27]
	v_cndmask_b32_e64 v93, v212, v93, s[68:69]
	s_mov_b64 s[68:69], s[24:25]
	v_cndmask_b32_e64 v92, v212, v92, s[66:67]
	s_mov_b64 s[66:67], 0x5a8080
	v_cndmask_b32_e64 v91, v212, v91, s[64:65]
	s_mov_b32 s65, 0x2aaaaaab
	s_movk_i32 s64, 0x41ff
	v_cndmask_b32_e64 v90, v212, v90, s[62:63]
	v_cndmask_b32_e64 v89, v212, v89, s[60:61]
	v_cndmask_b32_e64 v88, v212, v88, s[58:59]
	v_cndmask_b32_e64 v87, v212, v87, s[56:57]
	v_cndmask_b32_e64 v86, v212, v86, s[52:53]
	v_cndmask_b32_e64 v85, v212, v85, s[50:51]
	v_cndmask_b32_e64 v84, v212, v84, s[48:49]
	v_cndmask_b32_e64 v83, v212, v83, s[46:47]
	v_cndmask_b32_e64 v82, v212, v82, s[44:45]
	v_cndmask_b32_e64 v81, v212, v81, s[42:43]
	v_cndmask_b32_e64 v80, v212, v80, s[40:41]
	v_cndmask_b32_e32 v79, v212, v79, vcc
.LBB0_70:
	s_nop 9
	v_max3_f32 v166, v64, v65, v66
	v_max3_f32 v167, v67, v68, v69
	v_max3_f32 v166, v166, v70, v71
	v_max3_f32 v167, v167, v72, v73
	v_max3_f32 v166, v166, v74, v75
	v_max3_f32 v167, v167, v76, v77
	v_max3_f32 v166, v166, v78, v79
	v_max_f32_e32 v166, v166, v167
	s_nop 1
	v_max3_f32 v167, v80, v81, v82
	v_max3_f32 v168, v83, v84, v85
	v_max3_f32 v167, v167, v86, v87
	v_max3_f32 v168, v168, v88, v89
	v_max3_f32 v167, v167, v90, v91
	v_max3_f32 v168, v168, v92, v93
	v_max3_f32 v167, v167, v94, v95
	v_max3_f32 v166, v166, v167, v168
	v_mov_b32_e32 v167, v166
	s_nop 1
	v_permlane32_swap_b32_e32 v166, v167
	v_max3_f32 v165, v146, v166, v167
	v_sub_f32_e32 v166, v146, v165
	v_cmp_gt_f32_e32 vcc, 0xc1000000, v166
	s_cbranch_vccnz .Lattn_resc_72
	v_mov_b32_e32 v165, v146
	v_mov_b32_e32 v146, 1.0
	s_branch .LBB0_72
